# k35: k34 with all three register-staged K/V tiles in flight at loop entry (prologue wait vmcnt(6), loop wait vmcnt(4))
# speedup vs baseline: 1.0196x; 1.0020x over previous
; #define LAS __attribute__((address_space(3)))
; __device__ __forceinline__ float lane0(float v) { return __builtin_bit_cast(float, __builtin_amdgcn_readfirstlane(__builtin_bit_cast(int, v))); }
; __device__ __forceinline__ void attn_unit(const UnitDesc& u, LAS unsigned char* shm, float qkmax, float thresh) {
;     ...
;     const float ci = -Rown * LOG2E - qkmax;
;     const float kbq0 = Rq0 * LOG2E;
;     const int qabs = u.q0 + wid * 32 + r32;
;     float l_reg = 0.f; f32x16 o[2]; o[0] = f32x16{}; o[1] = f32x16{};
;     float lA = lfb[1], lB = lfb[2], lC = lfb[3];
;     { const float lf = lfb[0]; const float inc = inc4[0]; wsf[lane] = (inc - lf) * LOG2E; carry = lane0(inc);
;       *(LAS u32x4*)kdst = kreg; *(LAS u32x4*)vdst = vreg;
;       asm volatile("" : "+v"(qr[0]), "+v"(qr[1]), "+v"(qr[2]), "+v"(qr[3]));
;       asm volatile("s_waitcnt vmcnt(0)" : "+v"(kA), "+v"(vA), "+v"(kB), "+v"(vB), "+v"(kC), "+v"(vC) :: "memory"); }
;     int slot = 0, tile = NT - 1; bool stop = false;
.LBB0_772:
	v_lshlrev_b32_e32 v15, 1, v12
	s_lshl_b32 s12, s52, 10
	v_and_b32_e32 v15, 32, v15
	s_add_i32 s13, 0, 0x2000
	v_lshlrev_b32_e32 v142, 2, v136
	v_lshrrev_b32_e32 v12, 2, v12
	s_add_i32 s12, s12, 0
	v_add_u32_e32 v15, s13, v15
	v_and_or_b32 v12, v12, 3, v142
	s_lshl_b32 s13, s52, 9
	v_lshlrev_b32_e32 v12, 6, v12
	s_sub_i32 s53, s12, s13
	v_add_u32_e32 v147, s66, v10
	v_sub_f32_e32 v10, v0, v14
	v_lshl_add_u32 v143, v137, 4, s12
	v_add3_u32 v144, v15, v13, v12
	s_mov_b32 s12, 0xbfb8aa3b
	s_waitcnt lgkmcnt(0)
	v_mul_f32_e32 v146, 0x3fb8aa3b, v11
	v_mul_f32_e32 v10, 0x3fb8aa3b, v10
	v_lshl_add_u32 v11, v137, 2, s53
	v_mov_b32_e32 v14, v1
	v_mov_b32_e32 v15, v1
	v_lshlrev_b32_e32 v16, 10, v136
	v_lshlrev_b32_e32 v17, 4, v135
	v_fma_f32 v112, v21, s12, -v130
	v_mul_f32_e32 v197, 0x3fb8aa3b, v21
	s_mov_b64 s[98:99], 0
	s_nop 0
	v_readfirstlane_b32 s100, v197
	s_nop 3
	v_mov_b32_e32 v197, s100
	ds_write_b32 v11, v10 offset:32768
	v_readfirstlane_b32 s12, v0
	ds_write_b128 v143, v[2:5]
	ds_write_b128 v143, v[6:9] offset:8192
	v_mov_b32_e32 v0, v1
	v_mov_b32_e32 v2, v1
	v_mov_b32_e32 v3, v1
	v_mov_b32_e32 v4, v1
	v_mov_b32_e32 v5, v1
	v_mov_b32_e32 v6, v1
	v_mov_b32_e32 v7, v1
	v_mov_b32_e32 v8, v1
	v_mov_b32_e32 v9, v1
	v_mov_b32_e32 v10, v1
	v_mov_b32_e32 v11, v1
	v_mov_b32_e32 v12, v1
	v_mov_b32_e32 v13, v1
	v_mov_b64_e32 v[48:49], v[14:15]
	v_mov_b64_e32 v[64:65], v[14:15]
	v_mov_b64_e32 v[32:33], v[14:15]
	v_add3_u32 v145, 0, v16, v17
	s_add_i32 s73, s66, s49
	v_mov_b64_e32 v[46:47], v[12:13]
	v_mov_b64_e32 v[44:45], v[10:11]
	v_mov_b64_e32 v[42:43], v[8:9]
	v_mov_b64_e32 v[40:41], v[6:7]
	v_mov_b64_e32 v[38:39], v[4:5]
	v_mov_b64_e32 v[36:37], v[2:3]
	v_mov_b64_e32 v[34:35], v[0:1]
	v_mov_b64_e32 v[62:63], v[12:13]
	v_mov_b64_e32 v[60:61], v[10:11]
	v_mov_b64_e32 v[58:59], v[8:9]
	v_mov_b64_e32 v[56:57], v[6:7]
	v_mov_b64_e32 v[54:55], v[4:5]
	v_mov_b64_e32 v[52:53], v[2:3]
	v_mov_b64_e32 v[50:51], v[0:1]
	v_mov_b64_e32 v[30:31], v[12:13]
	v_mov_b64_e32 v[28:29], v[10:11]
	v_mov_b64_e32 v[26:27], v[8:9]
	v_mov_b64_e32 v[24:25], v[6:7]
	v_mov_b64_e32 v[22:23], v[4:5]
	v_mov_b64_e32 v[20:21], v[2:3]
	v_mov_b64_e32 v[18:19], v[0:1]
	v_mov_b64_e32 v[16:17], v[14:15]
	s_sub_i32 s72, s67, s28
	s_add_i32 s73, s73, 31
	v_mov_b32_e32 v113, v112
	v_mov_b32_e32 v114, v112
	v_mov_b32_e32 v115, v112
	v_mov_b32_e32 v116, v112
	v_mov_b32_e32 v117, v112
	v_mov_b32_e32 v118, v112
	v_mov_b32_e32 v119, v112
	v_mov_b32_e32 v120, v112
	v_mov_b32_e32 v121, v112
	v_mov_b32_e32 v122, v112
	v_mov_b32_e32 v123, v112
	v_mov_b32_e32 v124, v112
	v_mov_b32_e32 v125, v112
	v_mov_b32_e32 v126, v112
	v_mov_b32_e32 v127, v112
	s_lshl_b32 s75, s67, 6
	s_mov_b32 s70, 0
	v_mov_b32_e32 v148, 0
	s_mov_b64 s[62:63], 0
	v_mov_b32_e32 v150, s12
	v_mov_b64_e32 v[14:15], v[12:13]
	v_mov_b64_e32 v[12:13], v[10:11]
	v_mov_b64_e32 v[10:11], v[8:9]
	v_mov_b64_e32 v[8:9], v[6:7]
	v_mov_b64_e32 v[6:7], v[4:5]
	v_mov_b64_e32 v[4:5], v[2:3]
	v_mov_b64_e32 v[2:3], v[0:1]
	s_waitcnt vmcnt(6)
	s_branch .LBB0_777

.LBB0_777:
	s_waitcnt lgkmcnt(0)
	s_barrier
	s_waitcnt vmcnt(4)
	s_nop 1
	v_add_f32_dpp v0, v140, v140 row_shl:1 row_mask:0xf bank_mask:0xf bound_ctrl:1
	s_nop 1
	v_add_f32_dpp v0, v0, v0 row_shl:2 row_mask:0xf bank_mask:0xf bound_ctrl:1
	s_nop 1
	v_add_f32_dpp v0, v0, v0 row_shl:4 row_mask:0xf bank_mask:0xf bound_ctrl:1
	s_nop 1
	v_add_f32_dpp v0, v0, v0 row_shl:8 row_mask:0xf bank_mask:0xf bound_ctrl:1
	s_nop 0
	v_readlane_b32 s28, v0, 16
	v_readlane_b32 s67, v0, 32
	v_readlane_b32 s66, v0, 48
	s_and_saveexec_b64 s[12:13], s[6:7]
	s_xor_b64 s[12:13], exec, s[12:13]
	s_cbranch_execz .LBB0_783
	s_and_saveexec_b64 s[64:65], s[8:9]
	s_xor_b64 s[64:65], exec, s[64:65]
	v_mov_b32_e32 v149, s66
	v_cndmask_b32_e64 v149, 0, v149, s[10:11]
	s_andn2_saveexec_b64 s[64:65], s[64:65]
	v_mov_b32_e32 v149, s66
	v_add_f32_e32 v149, s67, v149
	s_or_b64 exec, exec, s[64:65]

; __device__ __forceinline__ void attn_unit(const UnitDesc& u, LAS unsigned char* shm, float qkmax, float thresh) {
;     ...
;     for (;;) {
;         ATT_ITER(kA, vA, lA); if (stop) break;
;         ATT_ITER(kB, vB, lB); if (stop) break;
.LBB0_792:
	s_cmp_lg_u32 s48, 0
	v_fma_f32 v151, v150, s50, -v146
	s_cselect_b64 s[64:65], -1, 0
	v_cmp_nlt_f32_e64 s[66:67], v151, -v131
	v_fma_f32 v196, v150, s50, -v197
	v_cmp_lt_f32_e64 s[100:101], v196, -v131
	s_nop 3
	s_or_b64 s[98:99], s[98:99], s[100:101]
	s_and_b64 s[68:69], s[64:65], s[66:67]
	s_mov_b64 s[66:67], -1
	s_and_saveexec_b64 s[64:65], s[68:69]
	s_cbranch_execz .LBB0_776
	s_waitcnt lgkmcnt(0)
	s_barrier
	s_waitcnt vmcnt(4)
	s_nop 1
	v_add_f32_dpp v151, v141, v141 row_shl:1 row_mask:0xf bank_mask:0xf bound_ctrl:1
	s_nop 1
	v_add_f32_dpp v151, v151, v151 row_shl:2 row_mask:0xf bank_mask:0xf bound_ctrl:1
	s_nop 1
	v_add_f32_dpp v151, v151, v151 row_shl:4 row_mask:0xf bank_mask:0xf bound_ctrl:1
	s_nop 1
	v_add_f32_dpp v152, v151, v151 row_shl:8 row_mask:0xf bank_mask:0xf bound_ctrl:1
	s_nop 0
	v_readlane_b32 s28, v152, 16
	v_readlane_b32 s79, v152, 32
	v_readlane_b32 s77, v152, 48
	s_and_saveexec_b64 s[66:67], s[6:7]
	s_xor_b64 s[66:67], exec, s[66:67]
	s_cbranch_execz .LBB0_799
	s_and_saveexec_b64 s[68:69], s[8:9]
	s_xor_b64 s[68:69], exec, s[68:69]
	v_mov_b32_e32 v151, s77
	v_cndmask_b32_e64 v153, 0, v151, s[10:11]
	s_andn2_saveexec_b64 s[68:69], s[68:69]
	v_mov_b32_e32 v151, s77
	v_add_f32_e32 v153, s79, v151
	s_or_b64 exec, exec, s[68:69]

; __device__ __forceinline__ void attn_unit(const UnitDesc& u, LAS unsigned char* shm, float qkmax, float thresh) {
;     ...
;     for (;;) {
;         ATT_ITER(kA, vA, lA); if (stop) break;
;         ATT_ITER(kB, vB, lB); if (stop) break;
;         ATT_ITER(kC, vC, lC); if (stop) break;
.LBB0_808:
	s_cmp_lg_u32 s48, 1
	v_fma_f32 v150, v151, s50, -v146
	s_cselect_b64 s[66:67], -1, 0
	v_cmp_nlt_f32_e64 s[68:69], v150, -v131
	v_fma_f32 v196, v151, s50, -v197
	v_cmp_lt_f32_e64 s[100:101], v196, -v131
	s_nop 3
	s_or_b64 s[98:99], s[98:99], s[100:101]
	s_and_b64 s[70:71], s[66:67], s[68:69]
	s_mov_b64 s[68:69], -1
	s_and_saveexec_b64 s[66:67], s[70:71]
	s_cbranch_execz .LBB0_775
	s_waitcnt lgkmcnt(0)
	s_barrier
	s_waitcnt vmcnt(4)
	s_nop 1
	v_add_f32_dpp v150, v139, v139 row_shl:1 row_mask:0xf bank_mask:0xf bound_ctrl:1
	s_nop 1
	v_add_f32_dpp v150, v150, v150 row_shl:2 row_mask:0xf bank_mask:0xf bound_ctrl:1
	s_nop 1
	v_add_f32_dpp v150, v150, v150 row_shl:4 row_mask:0xf bank_mask:0xf bound_ctrl:1
	s_nop 1
	v_add_f32_dpp v150, v150, v150 row_shl:8 row_mask:0xf bank_mask:0xf bound_ctrl:1
	s_nop 0
	v_readlane_b32 s28, v150, 16
	v_readlane_b32 s80, v150, 32
	v_readlane_b32 s78, v150, 48
	s_and_saveexec_b64 s[68:69], s[6:7]
	s_xor_b64 s[68:69], exec, s[68:69]
	s_cbranch_execz .LBB0_815
	s_and_saveexec_b64 s[70:71], s[8:9]
	s_xor_b64 s[70:71], exec, s[70:71]
	v_mov_b32_e32 v152, s78
	v_cndmask_b32_e64 v152, 0, v152, s[10:11]
	s_andn2_saveexec_b64 s[70:71], s[70:71]
	v_mov_b32_e32 v152, s78
	v_add_f32_e32 v152, s80, v152
	s_or_b64 exec, exec, s[70:71]
